# v31 + L6 GEMM: first K-loop iteration after an epilogue peeled, its first two waits allow the 16 epilogue stores to stay in flight (vmcnt 8+16)
# baseline (speedup 1.0000x reference)
; #define PG8_STAGE(bufoff, gbase, voff) do { _Pragma("unroll") for (int _i = 0; _i < 2; ++_i) \
;         __builtin_amdgcn_global_load_lds((const unsigned*)((const char*)(gbase) + (voff)[_i]), (LAS unsigned*)(lds + (bufoff) + ldsw + _i * 8192), 16, 0, 0); } while (0)
; #define PG8_WAIT_V(n) asm volatile("s_waitcnt vmcnt(" #n ")" ::: "memory")
; #define PG8_BAR __builtin_amdgcn_s_barrier()
; template <class Epi>
; __device__ __forceinline__ void gemm_phase(LAS unsigned char* lds, const Gemm g, const StaticOrder& S, const Epi& E, int wave_s) {
;     ...
;     const char* cA = (const char*)g.A + (size_t)cur.pm * tstepA; const char* cB = (const char*)g.Bt + (size_t)cur.pn * tstepB;
;     PG8_STAGE(PG8_SB(0, 0), cB, voffB); PG8_STAGE(PG8_SB(0, 1), cB + hstepB, voffB); PG8_STAGE(PG8_SA(0, 0), cA, voffA); PG8_STAGE(PG8_SA(0, 1), cA + hstepA, voffA);
;     if (wr == 1) PG8_BAR;
;     PG8_WAIT_V(2); PG8_BAR;
;     PG8_STAGE(PG8_SB(1, 0), cB + kstep, voffB); PG8_STAGE(PG8_SA(1, 0), cA + kstep, voffA); PG8_STAGE(PG8_SB(1, 1), cB + hstepB + kstep, voffB);
;     PG8_WAIT_V(6); PG8_BAR;
.LBB0_1038:
	v_mov_b32_e32 v135, v13
	v_lshl_add_u64 v[8:9], s[26:27], 0, v[134:135]
	v_mov_b32_e32 v131, v13
	v_readlane_b32 s22, v253, 55
	s_lshl_b32 s6, s6, 5
	v_lshl_add_u64 v[10:11], s[26:27], 0, v[130:131]
	v_mov_b32_e32 v137, v13
	v_readlane_b32 s23, v253, 56
	s_and_b32 s9, s6, 0x60
	s_add_i32 m0, s37, 0x18000
	v_lshl_add_u64 v[8:9], v[8:9], 0, s[84:85]
	v_lshl_add_u64 v[14:15], s[22:23], 0, v[136:137]
	v_mov_b32_e32 v133, v13
	s_lshl_b32 s8, s5, 13
	s_lshl_b32 s10, s9, 7
	s_waitcnt vmcnt(2)
	s_barrier
	global_load_lds_dwordx4 v[8:9], off
	v_lshl_add_u64 v[8:9], v[10:11], 0, s[84:85]
	s_add_i32 m0, s37, 0x1a000
	s_add_i32 s43, s37, 0x8000
	s_add_i32 s44, s37, 0xa000
	v_lshl_add_u64 v[16:17], s[22:23], 0, v[132:133]
	global_load_lds_dwordx4 v[8:9], off
	v_lshl_add_u64 v[8:9], v[14:15], 0, s[84:85]
	s_mov_b32 m0, s43
	s_add_u32 s6, s26, 0x40080
	global_load_lds_dwordx4 v[8:9], off
	v_lshl_add_u64 v[8:9], v[16:17], 0, s[84:85]
	s_mov_b32 m0, s44
	s_addc_u32 s7, s27, 0
	global_load_lds_dwordx4 v[8:9], off
	s_add_i32 m0, s37, 0x1c000
	v_lshl_add_u64 v[8:9], s[6:7], 0, v[134:135]
	global_load_lds_dwordx4 v[8:9], off
	v_lshl_add_u64 v[8:9], s[6:7], 0, v[130:131]
	s_add_i32 m0, s37, 0x1e000
	v_and_b32_e32 v7, 15, v0
	global_load_lds_dwordx4 v[8:9], off
	v_lshrrev_b32_e32 v8, 1, v0
	v_and_b32_e32 v8, 24, v8
	v_lshlrev_b32_e32 v9, 1, v8
	v_lshlrev_b32_e32 v0, 2, v0
	v_lshl_or_b32 v142, s5, 6, v7
	v_lshl_or_b32 v7, v7, 6, v9
	v_and_b32_e32 v0, 32, v0
	v_bitop3_b32 v9, v7, s8, v0 bitop3:0xde
	v_bitop3_b32 v143, v7, s10, v0 bitop3:0xde
	v_lshlrev_b32_e32 v0, 14, v5
	v_and_b32_e32 v0, 0xffff8000, v0
	v_lshl_add_u32 v0, v4, 11, v0
	v_and_b32_e32 v4, 1, v5
	v_lshl_or_b32 v0, v4, 6, v0
	v_lshl_add_u32 v138, v6, 1, v0
	v_lshlrev_b32_e32 v0, 14, v1
	v_and_b32_e32 v0, 0xffff8000, v0
	s_waitcnt vmcnt(6)
	v_lshl_add_u32 v0, v2, 11, v0
	v_and_b32_e32 v1, 1, v1
	s_cmpk_lt_u32 s4, 0x100
	v_lshl_or_b32 v0, v1, 6, v0
	v_readlane_b32 s4, v253, 53
	s_cselect_b64 s[6:7], -1, 0
	v_mov_b32_e32 v139, v13
	v_lshl_add_u32 v140, v3, 1, v0
	v_mov_b32_e32 v141, v13
	s_mov_b32 s45, 0
	v_add_u32_e32 v144, 0, v9
	s_lshl_b32 s20, s9, 1
	v_lshlrev_b32_e32 v12, 1, v8
	v_readlane_b32 s46, v253, 49
	s_mov_b32 s47, s4
	s_barrier
	v_readlane_b32 s5, v253, 54
	s_mov_b32 s100, 0
	s_branch .LBB0_1041

; #define PG8_WAIT_V(n) asm volatile("s_waitcnt vmcnt(" #n ")" ::: "memory")
; #define PG8_WAIT_L(n) asm volatile("s_waitcnt lgkmcnt(" #n ")" ::: "memory")
; template <class Epi>
; __device__ __forceinline__ void gemm_phase(LAS unsigned char* lds, const Gemm g, const StaticOrder& S, const Epi& E, int wave_s) {
;     ...
;         const bool has_next = S.next(ui + 1, nxt);
;         const char* nA = has_next ? (const char*)g.A + (size_t)nxt.pm * tstepA : cA; const char* nB = has_next ? (const char*)g.Bt + (size_t)nxt.pn * tstepB : cB;
;         for (int t = 0; t < nt; t += 2) {
;             const bool last = (t == nt - 2);
;             const char* a1 = cA + (size_t)(t + 1) * kstep;
;             const char* a2 = last ? nA : cA + (size_t)(t + 2) * kstep; const char* b2 = last ? nB : cB + (size_t)(t + 2) * kstep;
;             const char* a3 = a2 + kstep; const char* b3 = b2 + kstep;
;             PG8_LDB(B0, 0, 0); PG8_LDB(B1, 0, 1); PG8_SCHED; PG8_LDA(At, 0, 0); PG8_STAGE(PG8_SA(1, 1), a1 + hstepA, voffA);
;             PG8_WAIT_V(8); PG8_WAIT_L(0); PG8_BAR; PG8_MMA(0, 0, At, B0); PG8_MMA(0, 1, At, B1); PG8_BAR; PG8_SCHED;
;             PG8_LDA(At, 0, 1); PG8_STAGE(PG8_SB(0, 0), b2, voffB); PG8_STAGE(PG8_SB(0, 1), b2 + hstepB, voffB); PG8_STAGE(PG8_SA(0, 0), a2, voffA);
;             PG8_WAIT_V(8); PG8_WAIT_L(0); PG8_BAR; PG8_MMA(1, 0, At, B0); PG8_MMA(1, 1, At, B1); PG8_BAR; PG8_SCHED;
;             PG8_LDB(B0, 1, 0); PG8_LDB(B1, 1, 1); PG8_SCHED; PG8_LDA(At, 1, 0); PG8_STAGE(PG8_SA(0, 1), a2 + hstepA, voffA);
;             PG8_WAIT_V(8); PG8_WAIT_L(0); PG8_BAR; PG8_MMA(0, 0, At, B0); PG8_MMA(0, 1, At, B1); PG8_BAR; PG8_SCHED;
;             PG8_LDA(At, 1, 1); PG8_STAGE(PG8_SB(1, 0), b3, voffB); PG8_STAGE(PG8_SB(1, 1), b3 + hstepB, voffB); PG8_STAGE(PG8_SA(1, 0), a3, voffA);
;             PG8_WAIT_V(8); PG8_WAIT_L(0); PG8_BAR; PG8_MMA(1, 0, At, B0); PG8_MMA(1, 1, At, B1); PG8_BAR; PG8_SCHED;
;         }
;         if (wr == 0) PG8_BAR;
;         E(acc, cur, wr, wc, fr, fq);
;         if (!has_next) break;
; #pragma unroll
;         for (int a = 0; a < 2; ++a)
; #pragma unroll
;             for (int b = 0; b < 2; ++b)
; #pragma unroll
;                 for (int m = 0; m < 4; ++m)
; #pragma unroll
;                     for (int n = 0; n < 2; ++n) acc[a][b][m][n] = (f32x4){0.f, 0.f, 0.f, 0.f};
;         cur = nxt; cA = nA; cB = nB; ++ui;
.LBB0_1043:
	s_ashr_i32 s11, s10, 31
	s_lshl_b64 s[12:13], s[10:11], 19
	s_add_u32 s12, s74, s12
	s_addc_u32 s13, s75, s13
	s_and_b64 s[16:17], s[4:5], exec
	s_cselect_b32 s11, s13, s23
	s_cselect_b32 s48, s12, s22
	s_ashr_i32 s9, s8, 31
	s_lshl_b64 s[16:17], s[8:9], 19
	s_add_u32 s16, s18, s16
	s_addc_u32 s17, s35, s17
	s_and_b64 s[30:31], s[4:5], exec
	s_cselect_b32 s9, s17, s27
	s_cselect_b32 s49, s16, s26
	s_add_u32 s22, s22, 0x40080
	s_addc_u32 s23, s23, 0
	s_add_u32 s50, s26, 0x100
	v_mov_b32_e32 v0, 0
	s_addc_u32 s51, s27, 0
	s_mov_b32 s52, -2
	v_mov_b32_e32 v1, v0
	v_mov_b32_e32 v2, v0
	v_mov_b32_e32 v3, v0
	v_mov_b32_e32 v4, v0
	v_mov_b32_e32 v5, v0
	v_mov_b32_e32 v6, v0
	v_mov_b32_e32 v7, v0
	v_mov_b32_e32 v8, v0
	v_mov_b32_e32 v9, v0
	v_mov_b32_e32 v10, v0
	v_mov_b32_e32 v11, v0
	v_mov_b32_e32 v14, v0
	v_mov_b32_e32 v15, v0
	v_mov_b32_e32 v16, v0
	v_mov_b32_e32 v17, v0
	v_mov_b32_e32 v26, v0
	v_mov_b32_e32 v27, v0
	v_mov_b32_e32 v28, v0
	v_mov_b32_e32 v29, v0
	v_mov_b32_e32 v30, v0
	v_mov_b32_e32 v31, v0
	v_mov_b32_e32 v32, v0
	v_mov_b32_e32 v33, v0
	v_mov_b32_e32 v42, v0
	v_mov_b32_e32 v43, v0
	v_mov_b32_e32 v44, v0
	v_mov_b32_e32 v45, v0
	v_mov_b32_e32 v46, v0
	v_mov_b32_e32 v47, v0
	v_mov_b32_e32 v48, v0
	v_mov_b32_e32 v49, v0
	v_mov_b32_e32 v18, v0
	v_mov_b32_e32 v19, v0
	v_mov_b32_e32 v20, v0
	v_mov_b32_e32 v21, v0
	v_mov_b32_e32 v22, v0
	v_mov_b32_e32 v23, v0
	v_mov_b32_e32 v24, v0
	v_mov_b32_e32 v25, v0
	v_mov_b32_e32 v34, v0
	v_mov_b32_e32 v35, v0
	v_mov_b32_e32 v36, v0
	v_mov_b32_e32 v37, v0
	v_mov_b32_e32 v38, v0
	v_mov_b32_e32 v39, v0
	v_mov_b32_e32 v40, v0
	v_mov_b32_e32 v41, v0
	v_mov_b32_e32 v50, v0
	v_mov_b32_e32 v51, v0
	v_mov_b32_e32 v52, v0
	v_mov_b32_e32 v53, v0
	v_mov_b32_e32 v54, v0
	v_mov_b32_e32 v55, v0
	v_mov_b32_e32 v56, v0
	v_mov_b32_e32 v57, v0
	v_mov_b32_e32 v58, v0
	v_mov_b32_e32 v59, v0
	v_mov_b32_e32 v60, v0
	v_mov_b32_e32 v61, v0
	v_mov_b32_e32 v62, v0
	v_mov_b32_e32 v63, v0
	v_mov_b32_e32 v64, v0
	v_mov_b32_e32 v65, v0
	v_mov_b32_e32 v66, v0
	v_mov_b32_e32 v67, v0
	v_mov_b32_e32 v68, v0
	v_mov_b32_e32 v69, v0
	v_mov_b32_e32 v70, v0
	v_mov_b32_e32 v71, v0
	v_mov_b32_e32 v72, v0
	v_mov_b32_e32 v73, v0
	v_mov_b32_e32 v74, v0
	v_mov_b32_e32 v75, v0
	v_mov_b32_e32 v76, v0
	v_mov_b32_e32 v77, v0
	v_mov_b32_e32 v78, v0
	v_mov_b32_e32 v79, v0
	v_mov_b32_e32 v80, v0
	v_mov_b32_e32 v81, v0
	v_mov_b32_e32 v90, v0
	v_mov_b32_e32 v91, v0
	v_mov_b32_e32 v92, v0
	v_mov_b32_e32 v93, v0
	v_mov_b32_e32 v94, v0
	v_mov_b32_e32 v95, v0
	v_mov_b32_e32 v96, v0
	v_mov_b32_e32 v97, v0
	v_mov_b32_e32 v106, v0
	v_mov_b32_e32 v107, v0
	v_mov_b32_e32 v108, v0
	v_mov_b32_e32 v109, v0
	v_mov_b32_e32 v110, v0
	v_mov_b32_e32 v111, v0
	v_mov_b32_e32 v112, v0
	v_mov_b32_e32 v113, v0
	v_mov_b32_e32 v82, v0
	v_mov_b32_e32 v83, v0
	v_mov_b32_e32 v84, v0
	v_mov_b32_e32 v85, v0
	v_mov_b32_e32 v86, v0
	v_mov_b32_e32 v87, v0
	v_mov_b32_e32 v88, v0
	v_mov_b32_e32 v89, v0
	v_mov_b32_e32 v98, v0
	v_mov_b32_e32 v99, v0
	v_mov_b32_e32 v100, v0
	v_mov_b32_e32 v101, v0
	v_mov_b32_e32 v102, v0
	v_mov_b32_e32 v103, v0
	v_mov_b32_e32 v104, v0
	v_mov_b32_e32 v105, v0
	v_mov_b32_e32 v114, v0
	v_mov_b32_e32 v115, v0
	v_mov_b32_e32 v116, v0
	v_mov_b32_e32 v117, v0
	v_mov_b32_e32 v118, v0
	v_mov_b32_e32 v119, v0
	v_mov_b32_e32 v120, v0
	v_mov_b32_e32 v121, v0
	v_mov_b32_e32 v122, v0
	v_mov_b32_e32 v123, v0
	v_mov_b32_e32 v124, v0
	v_mov_b32_e32 v125, v0
	v_mov_b32_e32 v126, v0
	v_mov_b32_e32 v127, v0
	v_mov_b32_e32 v128, v0
	v_mov_b32_e32 v129, v0
	s_cmp_lg_u32 s100, 0
	s_cbranch_scc1 .Lg6_first

; __device__ __forceinline__ unsigned pk2(float lo, float hi) { f32x2 v = {lo, hi}; bf16x2_t b = __builtin_convertvector(v, bf16x2_t); return __builtin_bit_cast(unsigned, b); }
; #define PG8_BAR __builtin_amdgcn_s_barrier()
; template <class Epi>
; __device__ __forceinline__ void gemm_phase(LAS unsigned char* lds, const Gemm g, const StaticOrder& S, const Epi& E, int wave_s) {
;     ...
;         if (wr == 0) PG8_BAR;
;         E(acc, cur, wr, wc, fr, fq);
;         if (!has_next) break;
; #pragma unroll
;         for (int a = 0; a < 2; ++a)
; #pragma unroll
;             for (int b = 0; b < 2; ++b)
; #pragma unroll
;                 for (int m = 0; m < 4; ++m)
; #pragma unroll
;                     for (int n = 0; n < 2; ++n) acc[a][b][m][n] = (f32x4){0.f, 0.f, 0.f, 0.f};
;         cur = nxt; cA = nA; cB = nB; ++ui;
;         if (wr == 1) PG8_BAR;
;     }
;     __device__ __forceinline__ void operator()(const f32x4 (&acc)[2][2][4][2], const Unit& u, int wr, int wc, int fr, int fq) const {
; #pragma unroll
;         for (int ai = 0; ai < 2; ++ai)
; #pragma unroll
;             for (int m = 0; m < 4; ++m) {
;                 bf16_t* rowp = O + (size_t)(u.pm * BM + ai * HALF + wr * 64 + m * 16 + fr) * ldc + u.pn * BM + wc * 32 + 8 * fq;
; #pragma unroll
;                 for (int bj = 0; bj < 2; ++bj) { const f32x4 v0 = acc[ai][bj][m][0], v1 = acc[ai][bj][m][1];
;                     u32x4 w; w.x = pk2(v0[0], v0[1]); w.y = pk2(v0[2], v0[3]); w.z = pk2(v1[0], v1[1]); w.w = pk2(v1[2], v1[3]);
;                     *(u32x4*)(rowp + bj * HALF) = w; }
;             }
;     }
.Lg6_after:
	s_and_b64 vcc, exec, s[6:7]
	s_cbranch_vccz .LBB0_1047
	s_barrier
.LBB0_1047:
	v_lshl_add_u32 v145, s47, 8, v142
	s_lshl_b32 s22, s46, 8
	s_ashr_i32 s23, s22, 31
	v_mov_b64_e32 v[146:147], s[72:73]
	v_cvt_pk_bf16_f32 v70, v70, v71
	v_cvt_pk_bf16_f32 v71, v72, v73
	v_cvt_pk_bf16_f32 v72, v66, v67
	v_add_u32_e32 v66, 0x80, v145
	v_mad_i64_i32 v[148:149], s[26:27], v145, s67, v[146:147]
	s_lshl_b64 s[22:23], s[22:23], 1
	v_cvt_pk_bf16_f32 v110, v110, v111
	v_cvt_pk_bf16_f32 v111, v112, v113
	v_cvt_pk_bf16_f32 v112, v106, v107
	v_or_b32_e32 v106, 16, v145
	v_mad_i64_i32 v[66:67], s[26:27], v66, s67, v[146:147]
	v_cvt_pk_bf16_f32 v46, v46, v47
	v_cvt_pk_bf16_f32 v47, v48, v49
	v_cvt_pk_bf16_f32 v48, v42, v43
	v_add_u32_e32 v42, 0x90, v145
	v_lshl_add_u64 v[148:149], v[148:149], 0, s[22:23]
	v_mad_i64_i32 v[106:107], s[26:27], v106, s67, v[146:147]
	v_cvt_pk_bf16_f32 v94, v94, v95
	v_cvt_pk_bf16_f32 v95, v96, v97
	v_cvt_pk_bf16_f32 v96, v90, v91
	v_or_b32_e32 v90, 32, v145
	v_lshl_add_u64 v[66:67], v[66:67], 0, s[22:23]
	v_mad_i64_i32 v[42:43], s[26:27], v42, s67, v[146:147]
	v_cvt_pk_bf16_f32 v30, v30, v31
	v_cvt_pk_bf16_f32 v31, v32, v33
	v_cvt_pk_bf16_f32 v32, v26, v27
	v_add_u32_e32 v26, 0xa0, v145
	v_lshl_add_u64 v[148:149], v[148:149], 0, s[20:21]
	v_lshl_add_u64 v[106:107], v[106:107], 0, s[22:23]
	v_mad_i64_i32 v[90:91], s[26:27], v90, s67, v[146:147]
	v_cvt_pk_bf16_f32 v78, v78, v79
	v_cvt_pk_bf16_f32 v79, v80, v81
	v_cvt_pk_bf16_f32 v80, v74, v75
	v_or_b32_e32 v74, 48, v145
	v_lshl_add_u64 v[66:67], v[66:67], 0, s[20:21]
	v_lshl_add_u64 v[42:43], v[42:43], 0, s[22:23]
	v_mad_i64_i32 v[26:27], s[26:27], v26, s67, v[146:147]
	v_cvt_pk_bf16_f32 v14, v14, v15
	v_cvt_pk_bf16_f32 v15, v16, v17
	v_cvt_pk_bf16_f32 v16, v8, v9
	v_add_u32_e32 v8, 0xb0, v145
	v_lshl_add_u64 v[148:149], v[148:149], 0, v[12:13]
	v_cvt_pk_bf16_f32 v113, v108, v109
	v_lshl_add_u64 v[106:107], v[106:107], 0, s[20:21]
	v_lshl_add_u64 v[90:91], v[90:91], 0, s[22:23]
	v_mad_i64_i32 v[74:75], s[26:27], v74, s67, v[146:147]
	v_lshl_add_u64 v[66:67], v[66:67], 0, v[12:13]
	v_cvt_pk_bf16_f32 v49, v44, v45
	v_lshl_add_u64 v[42:43], v[42:43], 0, s[20:21]
	v_lshl_add_u64 v[26:27], v[26:27], 0, s[22:23]
	v_mad_i64_i32 v[8:9], s[26:27], v8, s67, v[146:147]
	global_store_dwordx4 v[148:149], v[110:113], off offset:256
	v_cvt_pk_bf16_f32 v97, v92, v93
	v_lshl_add_u64 v[90:91], v[90:91], 0, s[20:21]
	v_lshl_add_u64 v[110:111], v[106:107], 0, v[12:13]
	v_lshl_add_u64 v[74:75], v[74:75], 0, s[22:23]
	global_store_dwordx4 v[66:67], v[46:49], off offset:256
	v_cvt_pk_bf16_f32 v33, v28, v29
	v_lshl_add_u64 v[26:27], v[26:27], 0, s[20:21]
	v_lshl_add_u64 v[46:47], v[42:43], 0, v[12:13]
	v_lshl_add_u64 v[8:9], v[8:9], 0, s[22:23]
	global_store_dwordx4 v[110:111], v[94:97], off offset:256
	v_cvt_pk_bf16_f32 v81, v76, v77
	v_lshl_add_u64 v[74:75], v[74:75], 0, s[20:21]
	v_lshl_add_u64 v[94:95], v[90:91], 0, v[12:13]
	global_store_dwordx4 v[46:47], v[30:33], off offset:256
	v_cvt_pk_bf16_f32 v17, v10, v11
	v_lshl_add_u64 v[8:9], v[8:9], 0, s[20:21]
	v_lshl_add_u64 v[30:31], v[26:27], 0, v[12:13]
	v_cvt_pk_bf16_f32 v126, v126, v127
	v_cvt_pk_bf16_f32 v127, v128, v129
	v_cvt_pk_bf16_f32 v128, v122, v123
	v_cvt_pk_bf16_f32 v129, v124, v125
	v_cvt_pk_bf16_f32 v106, v118, v119
	v_cvt_pk_bf16_f32 v107, v120, v121
	v_cvt_pk_bf16_f32 v108, v114, v115
	v_cvt_pk_bf16_f32 v109, v116, v117
	v_cvt_pk_bf16_f32 v90, v102, v103
	v_cvt_pk_bf16_f32 v91, v104, v105
	v_cvt_pk_bf16_f32 v92, v98, v99
	v_cvt_pk_bf16_f32 v93, v100, v101
	global_store_dwordx4 v[94:95], v[78:81], off offset:256
	v_cvt_pk_bf16_f32 v76, v82, v83
	v_cvt_pk_bf16_f32 v77, v84, v85
	v_lshl_add_u64 v[78:79], v[74:75], 0, v[12:13]
	v_cvt_pk_bf16_f32 v74, v86, v87
	v_cvt_pk_bf16_f32 v75, v88, v89
	v_cvt_pk_bf16_f32 v73, v68, v69
	v_cvt_pk_bf16_f32 v62, v62, v63
	v_cvt_pk_bf16_f32 v63, v64, v65
	v_cvt_pk_bf16_f32 v64, v58, v59
	v_cvt_pk_bf16_f32 v65, v60, v61
	v_cvt_pk_bf16_f32 v42, v54, v55
	v_cvt_pk_bf16_f32 v43, v56, v57
	v_cvt_pk_bf16_f32 v44, v50, v51
	v_cvt_pk_bf16_f32 v45, v52, v53
	v_cvt_pk_bf16_f32 v26, v38, v39
	v_cvt_pk_bf16_f32 v27, v40, v41
	v_cvt_pk_bf16_f32 v28, v34, v35
	v_cvt_pk_bf16_f32 v29, v36, v37
	global_store_dwordx4 v[30:31], v[14:17], off offset:256
	v_cvt_pk_bf16_f32 v10, v18, v19
	v_cvt_pk_bf16_f32 v11, v20, v21
	v_lshl_add_u64 v[14:15], v[8:9], 0, v[12:13]
	v_cvt_pk_bf16_f32 v8, v22, v23
	v_cvt_pk_bf16_f32 v9, v24, v25
	v_cvt_pk_bf16_f32 v4, v4, v5
	v_cvt_pk_bf16_f32 v5, v6, v7
	v_cvt_pk_bf16_f32 v6, v0, v1
	v_cvt_pk_bf16_f32 v7, v2, v3
	s_andn2_b64 vcc, exec, s[4:5]
	s_mov_b64 s[4:5], -1
	global_store_dwordx4 v[148:149], v[126:129], off
	global_store_dwordx4 v[110:111], v[106:109], off
	global_store_dwordx4 v[94:95], v[90:93], off
	global_store_dwordx4 v[78:79], v[74:77], off
	global_store_dwordx4 v[78:79], v[70:73], off offset:256
	global_store_dwordx4 v[66:67], v[62:65], off
	global_store_dwordx4 v[46:47], v[42:45], off
	global_store_dwordx4 v[30:31], v[26:29], off
	global_store_dwordx4 v[14:15], v[8:11], off
	global_store_dwordx4 v[14:15], v[4:7], off offset:256
	s_mov_b32 s100, 1
	s_cbranch_vccnz .LBB0_1040
	s_andn2_b64 vcc, exec, s[0:1]
	s_cbranch_vccnz .LBB0_1039
	s_barrier
	s_branch .LBB0_1039
; #define PG8_STAGE(bufoff, gbase, voff) do { _Pragma("unroll") for (int _i = 0; _i < 2; ++_i) \
;         __builtin_amdgcn_global_load_lds((const unsigned*)((const char*)(gbase) + (voff)[_i]), (LAS unsigned*)(lds + (bufoff) + ldsw + _i * 8192), 16, 0, 0); } while (0)
; #define PG8_LDA(dst, b, h) do { _Pragma("unroll") for (int m = 0; m < 4; ++m) _Pragma("unroll") for (int k = 0; k < 2; ++k) dst[m][k] = *(const LAS bf16x8*)(lds + PG8_SA(b, h) + aoff + m * 2048 + k * 1024); } while (0)
; #define PG8_LDB(dst, b, h) do { _Pragma("unroll") for (int n = 0; n < 2; ++n) _Pragma("unroll") for (int k = 0; k < 2; ++k) dst[n][k] = *(const LAS bf16x8*)(lds + PG8_SB(b, h) + boff + n * 2048 + k * 1024); } while (0)
; #define PG8_MMA(ai, bj, At, Bt) do { __builtin_amdgcn_s_setprio(1); _Pragma("unroll") for (int m = 0; m < 4; ++m) _Pragma("unroll") for (int n = 0; n < 2; ++n) _Pragma("unroll") for (int k = 0; k < 2; ++k) \
;         acc[ai][bj][m][n] = __builtin_amdgcn_mfma_f32_16x16x32_bf16(Bt[n][k], At[m][k], acc[ai][bj][m][n], 0, 0, 0); __builtin_amdgcn_s_setprio(0); } while (0)
; #define PG8_WAIT_V(n) asm volatile("s_waitcnt vmcnt(" #n ")" ::: "memory")
; #define PG8_WAIT_L(n) asm volatile("s_waitcnt lgkmcnt(" #n ")" ::: "memory")
; #define PG8_BAR __builtin_amdgcn_s_barrier()
; #define PG8_SCHED __builtin_amdgcn_sched_barrier(0)
; template <class Epi>
; __device__ __forceinline__ void gemm_phase(LAS unsigned char* lds, const Gemm g, const StaticOrder& S, const Epi& E, int wave_s) {
;     ...
;             PG8_LDB(B0, 0, 0); PG8_LDB(B1, 0, 1); PG8_SCHED; PG8_LDA(At, 0, 0); PG8_STAGE(PG8_SA(1, 1), a1 + hstepA, voffA);
;             PG8_WAIT_V(8); PG8_WAIT_L(0); PG8_BAR; PG8_MMA(0, 0, At, B0); PG8_MMA(0, 1, At, B1); PG8_BAR; PG8_SCHED;
;             PG8_LDA(At, 0, 1); PG8_STAGE(PG8_SB(0, 0), b2, voffB); PG8_STAGE(PG8_SB(0, 1), b2 + hstepB, voffB); PG8_STAGE(PG8_SA(0, 0), a2, voffA);
;             PG8_WAIT_V(8); PG8_WAIT_L(0); PG8_BAR; PG8_MMA(1, 0, At, B0); PG8_MMA(1, 1, At, B1); PG8_BAR; PG8_SCHED;
.Lg6_first:
	s_add_u32 s26, s22, 0xfffc0080
	s_addc_u32 s27, s23, -1
	s_add_i32 s53, 0, 0x10000
	s_cmp_eq_u32 s52, 12
	s_cselect_b32 s31, s11, s27
	s_cselect_b32 s30, s48, s26
	v_add_u32_e32 v145, s53, v143
	s_cselect_b32 s27, s9, s51
	s_cselect_b32 s26, s49, s50
	s_add_i32 s54, 0, 0x14000
	ds_read_b128 v[146:149], v145
	ds_read_b128 v[150:153], v145 offset:1024
	ds_read_b128 v[154:157], v145 offset:2048
	ds_read_b128 v[158:161], v145 offset:3072
	v_add_u32_e32 v145, s54, v143
	ds_read_b128 v[162:165], v145
	ds_read_b128 v[166:169], v145 offset:1024
	ds_read_b128 v[170:173], v145 offset:2048
	ds_read_b128 v[178:181], v145 offset:3072
	v_lshl_add_u64 v[174:175], s[22:23], 0, v[138:139]
	s_add_i32 m0, s37, 0xc000
	ds_read_b128 v[182:185], v144
	ds_read_b128 v[186:189], v144 offset:1024
	ds_read_b128 v[190:193], v144 offset:2048
	ds_read_b128 v[194:197], v144 offset:3072
	ds_read_b128 v[198:201], v144 offset:4096
	ds_read_b128 v[202:205], v144 offset:5120
	ds_read_b128 v[206:209], v144 offset:6144
	ds_read_b128 v[210:213], v144 offset:7168
	global_load_lds_dwordx4 v[174:175], off
	v_lshl_add_u64 v[174:175], s[22:23], 0, v[140:141]
	s_add_i32 m0, s37, 0xe000
	s_nop 0
	global_load_lds_dwordx4 v[174:175], off
	s_waitcnt vmcnt(24)
	s_waitcnt lgkmcnt(0)
	s_barrier
	s_setprio 1
	s_waitcnt lgkmcnt(0)
	v_mfma_f32_16x16x32_bf16 v[126:129], v[146:149], v[182:185], v[126:129]
	v_mfma_f32_16x16x32_bf16 v[122:125], v[154:157], v[182:185], v[122:125]
	v_mfma_f32_16x16x32_bf16 v[118:121], v[146:149], v[190:193], v[118:121]
	v_mfma_f32_16x16x32_bf16 v[114:117], v[154:157], v[190:193], v[114:117]
	v_mfma_f32_16x16x32_bf16 v[102:105], v[146:149], v[198:201], v[102:105]
	v_mfma_f32_16x16x32_bf16 v[98:101], v[154:157], v[198:201], v[98:101]
	v_mfma_f32_16x16x32_bf16 v[86:89], v[146:149], v[206:209], v[86:89]
	v_mfma_f32_16x16x32_bf16 v[82:85], v[154:157], v[206:209], v[82:85]
	v_mfma_f32_16x16x32_bf16 v[126:129], v[150:153], v[186:189], v[126:129]
	v_mfma_f32_16x16x32_bf16 v[122:125], v[158:161], v[186:189], v[122:125]
	v_mfma_f32_16x16x32_bf16 v[118:121], v[150:153], v[194:197], v[118:121]
	v_mfma_f32_16x16x32_bf16 v[114:117], v[158:161], v[194:197], v[114:117]
	v_mfma_f32_16x16x32_bf16 v[102:105], v[150:153], v[202:205], v[102:105]
	v_mfma_f32_16x16x32_bf16 v[98:101], v[158:161], v[202:205], v[98:101]
	v_mfma_f32_16x16x32_bf16 v[86:89], v[150:153], v[210:213], v[86:89]
	v_mfma_f32_16x16x32_bf16 v[82:85], v[158:161], v[210:213], v[82:85]
	s_setprio 0
	s_setprio 1
	v_mfma_f32_16x16x32_bf16 v[110:113], v[162:165], v[182:185], v[110:113]
	v_mfma_f32_16x16x32_bf16 v[106:109], v[170:173], v[182:185], v[106:109]
	v_mfma_f32_16x16x32_bf16 v[94:97], v[162:165], v[190:193], v[94:97]
	v_mfma_f32_16x16x32_bf16 v[90:93], v[170:173], v[190:193], v[90:93]
	v_mfma_f32_16x16x32_bf16 v[78:81], v[162:165], v[198:201], v[78:81]
	v_mfma_f32_16x16x32_bf16 v[74:77], v[170:173], v[198:201], v[74:77]
	v_mfma_f32_16x16x32_bf16 v[70:73], v[162:165], v[206:209], v[70:73]
	v_mfma_f32_16x16x32_bf16 v[66:69], v[170:173], v[206:209], v[66:69]
	v_mfma_f32_16x16x32_bf16 v[110:113], v[166:169], v[186:189], v[110:113]
	v_mfma_f32_16x16x32_bf16 v[106:109], v[178:181], v[186:189], v[106:109]
	v_mfma_f32_16x16x32_bf16 v[94:97], v[166:169], v[194:197], v[94:97]
	v_mfma_f32_16x16x32_bf16 v[90:93], v[178:181], v[194:197], v[90:93]
	v_mfma_f32_16x16x32_bf16 v[78:81], v[166:169], v[202:205], v[78:81]
	v_mfma_f32_16x16x32_bf16 v[74:77], v[178:181], v[202:205], v[74:77]
	v_mfma_f32_16x16x32_bf16 v[70:73], v[166:169], v[210:213], v[70:73]
	v_mfma_f32_16x16x32_bf16 v[66:69], v[178:181], v[210:213], v[66:69]
	s_setprio 0
	s_barrier
	s_add_i32 s53, s53, s36
	v_lshl_add_u64 v[174:175], s[26:27], 0, v[134:135]
	s_mov_b32 m0, s53
	ds_read_b128 v[182:185], v144 offset:16384
	ds_read_b128 v[186:189], v144 offset:17408
	ds_read_b128 v[190:193], v144 offset:18432
	ds_read_b128 v[194:197], v144 offset:19456
	ds_read_b128 v[198:201], v144 offset:20480
	ds_read_b128 v[202:205], v144 offset:21504
	ds_read_b128 v[206:209], v144 offset:22528
	ds_read_b128 v[210:213], v144 offset:23552
	global_load_lds_dwordx4 v[174:175], off
	s_add_i32 m0, s53, 0x2000
	s_add_u32 s58, s26, 0x40000
	v_lshl_add_u64 v[176:177], s[26:27], 0, v[130:131]
	s_addc_u32 s59, s27, 0
	s_add_i32 s53, s54, s36
	global_load_lds_dwordx4 v[176:177], off
	v_lshl_add_u64 v[214:215], s[58:59], 0, v[134:135]
	s_mov_b32 m0, s53
	v_lshl_add_u64 v[216:217], s[30:31], 0, v[132:133]
	global_load_lds_dwordx4 v[214:215], off
	v_lshl_add_u64 v[214:215], s[58:59], 0, v[130:131]
	s_add_i32 m0, s53, 0x2000
	s_nop 0
	global_load_lds_dwordx4 v[214:215], off
	v_lshl_add_u64 v[214:215], s[30:31], 0, v[136:137]
	s_mov_b32 m0, s37
	s_nop 0
	global_load_lds_dwordx4 v[214:215], off
	s_mov_b32 m0, s40
	s_nop 0
	global_load_lds_dwordx4 v[216:217], off
	s_waitcnt vmcnt(24)
	s_waitcnt lgkmcnt(0)
	s_barrier
; #define PG8_STAGE(bufoff, gbase, voff) do { _Pragma("unroll") for (int _i = 0; _i < 2; ++_i) \
;         __builtin_amdgcn_global_load_lds((const unsigned*)((const char*)(gbase) + (voff)[_i]), (LAS unsigned*)(lds + (bufoff) + ldsw + _i * 8192), 16, 0, 0); } while (0)
; #define PG8_LDA(dst, b, h) do { _Pragma("unroll") for (int m = 0; m < 4; ++m) _Pragma("unroll") for (int k = 0; k < 2; ++k) dst[m][k] = *(const LAS bf16x8*)(lds + PG8_SA(b, h) + aoff + m * 2048 + k * 1024); } while (0)
; #define PG8_LDB(dst, b, h) do { _Pragma("unroll") for (int n = 0; n < 2; ++n) _Pragma("unroll") for (int k = 0; k < 2; ++k) dst[n][k] = *(const LAS bf16x8*)(lds + PG8_SB(b, h) + boff + n * 2048 + k * 1024); } while (0)
; #define PG8_MMA(ai, bj, At, Bt) do { __builtin_amdgcn_s_setprio(1); _Pragma("unroll") for (int m = 0; m < 4; ++m) _Pragma("unroll") for (int n = 0; n < 2; ++n) _Pragma("unroll") for (int k = 0; k < 2; ++k) \
;         acc[ai][bj][m][n] = __builtin_amdgcn_mfma_f32_16x16x32_bf16(Bt[n][k], At[m][k], acc[ai][bj][m][n], 0, 0, 0); __builtin_amdgcn_s_setprio(0); } while (0)
; #define PG8_WAIT_V(n) asm volatile("s_waitcnt vmcnt(" #n ")" ::: "memory")
; #define PG8_WAIT_L(n) asm volatile("s_waitcnt lgkmcnt(" #n ")" ::: "memory")
; #define PG8_BAR __builtin_amdgcn_s_barrier()
; #define PG8_SCHED __builtin_amdgcn_sched_barrier(0)
; template <class Epi>
; __device__ __forceinline__ void gemm_phase(LAS unsigned char* lds, const Gemm g, const StaticOrder& S, const Epi& E, int wave_s) {
;     ...
;             PG8_WAIT_V(8); PG8_WAIT_L(0); PG8_BAR; PG8_MMA(1, 0, At, B0); PG8_MMA(1, 1, At, B1); PG8_BAR; PG8_SCHED;
;             PG8_LDB(B0, 1, 0); PG8_LDB(B1, 1, 1); PG8_SCHED; PG8_LDA(At, 1, 0); PG8_STAGE(PG8_SA(0, 1), a2 + hstepA, voffA);
;             PG8_WAIT_V(8); PG8_WAIT_L(0); PG8_BAR; PG8_MMA(0, 0, At, B0); PG8_MMA(0, 1, At, B1); PG8_BAR; PG8_SCHED;
;             PG8_LDA(At, 1, 1); PG8_STAGE(PG8_SB(1, 0), b3, voffB); PG8_STAGE(PG8_SB(1, 1), b3 + hstepB, voffB); PG8_STAGE(PG8_SA(1, 0), a3, voffA);
;             PG8_WAIT_V(8); PG8_WAIT_L(0); PG8_BAR; PG8_MMA(1, 0, At, B0); PG8_MMA(1, 1, At, B1); PG8_BAR; PG8_SCHED;
	s_setprio 1
	s_waitcnt lgkmcnt(0)
	v_mfma_f32_16x16x32_bf16 v[62:65], v[146:149], v[182:185], v[62:65]
	v_mfma_f32_16x16x32_bf16 v[58:61], v[154:157], v[182:185], v[58:61]
	v_mfma_f32_16x16x32_bf16 v[54:57], v[146:149], v[190:193], v[54:57]
	v_mfma_f32_16x16x32_bf16 v[50:53], v[154:157], v[190:193], v[50:53]
	v_mfma_f32_16x16x32_bf16 v[38:41], v[146:149], v[198:201], v[38:41]
	v_mfma_f32_16x16x32_bf16 v[34:37], v[154:157], v[198:201], v[34:37]
	v_mfma_f32_16x16x32_bf16 v[22:25], v[146:149], v[206:209], v[22:25]
	v_mfma_f32_16x16x32_bf16 v[18:21], v[154:157], v[206:209], v[18:21]
	v_mfma_f32_16x16x32_bf16 v[62:65], v[150:153], v[186:189], v[62:65]
	v_mfma_f32_16x16x32_bf16 v[58:61], v[158:161], v[186:189], v[58:61]
	v_mfma_f32_16x16x32_bf16 v[54:57], v[150:153], v[194:197], v[54:57]
	v_mfma_f32_16x16x32_bf16 v[50:53], v[158:161], v[194:197], v[50:53]
	v_mfma_f32_16x16x32_bf16 v[38:41], v[150:153], v[202:205], v[38:41]
	v_mfma_f32_16x16x32_bf16 v[34:37], v[158:161], v[202:205], v[34:37]
	v_mfma_f32_16x16x32_bf16 v[22:25], v[150:153], v[210:213], v[22:25]
	v_mfma_f32_16x16x32_bf16 v[18:21], v[158:161], v[210:213], v[18:21]
	s_setprio 0
	s_setprio 1
	v_mfma_f32_16x16x32_bf16 v[46:49], v[162:165], v[182:185], v[46:49]
	v_mfma_f32_16x16x32_bf16 v[42:45], v[170:173], v[182:185], v[42:45]
	v_mfma_f32_16x16x32_bf16 v[30:33], v[162:165], v[190:193], v[30:33]
	v_mfma_f32_16x16x32_bf16 v[26:29], v[170:173], v[190:193], v[26:29]
	v_mfma_f32_16x16x32_bf16 v[14:17], v[162:165], v[198:201], v[14:17]
	v_mfma_f32_16x16x32_bf16 v[8:11], v[170:173], v[198:201], v[8:11]
	v_mfma_f32_16x16x32_bf16 v[4:7], v[162:165], v[206:209], v[4:7]
	v_mfma_f32_16x16x32_bf16 v[0:3], v[170:173], v[206:209], v[0:3]
	v_mfma_f32_16x16x32_bf16 v[46:49], v[166:169], v[186:189], v[46:49]
	v_mfma_f32_16x16x32_bf16 v[42:45], v[178:181], v[186:189], v[42:45]
	v_mfma_f32_16x16x32_bf16 v[30:33], v[166:169], v[194:197], v[30:33]
	v_mfma_f32_16x16x32_bf16 v[26:29], v[178:181], v[194:197], v[26:29]
	v_mfma_f32_16x16x32_bf16 v[14:17], v[166:169], v[202:205], v[14:17]
	v_mfma_f32_16x16x32_bf16 v[8:11], v[178:181], v[202:205], v[8:11]
	v_mfma_f32_16x16x32_bf16 v[4:7], v[166:169], v[210:213], v[4:7]
	v_mfma_f32_16x16x32_bf16 v[0:3], v[178:181], v[210:213], v[0:3]
	s_setprio 0
	s_barrier
	s_add_i32 s53, 0, 0x18000
	v_add_u32_e32 v145, s53, v143
	s_add_i32 s54, 0, 0x1c000
	ds_read_b128 v[146:149], v145
	ds_read_b128 v[150:153], v145 offset:1024
	ds_read_b128 v[154:157], v145 offset:2048
	ds_read_b128 v[158:161], v145 offset:3072
	v_add_u32_e32 v145, s54, v143
	ds_read_b128 v[162:165], v145
	ds_read_b128 v[166:169], v145 offset:1024
	ds_read_b128 v[170:173], v145 offset:2048
	ds_read_b128 v[178:181], v145 offset:3072
	s_add_u32 s30, s30, 0x40000
	s_addc_u32 s31, s31, 0
	s_mov_b32 m0, s41
	v_lshl_add_u64 v[218:219], s[30:31], 0, v[136:137]
	ds_read_b128 v[182:185], v144 offset:32768
	ds_read_b128 v[186:189], v144 offset:33792
	ds_read_b128 v[190:193], v144 offset:34816
	ds_read_b128 v[194:197], v144 offset:35840
	ds_read_b128 v[198:201], v144 offset:36864
	ds_read_b128 v[202:205], v144 offset:37888
	ds_read_b128 v[206:209], v144 offset:38912
	ds_read_b128 v[210:213], v144 offset:39936
	global_load_lds_dwordx4 v[218:219], off
	v_lshl_add_u64 v[218:219], s[30:31], 0, v[132:133]
	s_mov_b32 m0, s42
	s_nop 0
	global_load_lds_dwordx4 v[218:219], off
	s_waitcnt vmcnt(8)
	s_waitcnt lgkmcnt(0)
	s_barrier
	s_setprio 1
	s_waitcnt lgkmcnt(0)
	v_mfma_f32_16x16x32_bf16 v[126:129], v[146:149], v[182:185], v[126:129]
	v_mfma_f32_16x16x32_bf16 v[122:125], v[154:157], v[182:185], v[122:125]
	v_mfma_f32_16x16x32_bf16 v[118:121], v[146:149], v[190:193], v[118:121]
	v_mfma_f32_16x16x32_bf16 v[114:117], v[154:157], v[190:193], v[114:117]
	v_mfma_f32_16x16x32_bf16 v[102:105], v[146:149], v[198:201], v[102:105]
	v_mfma_f32_16x16x32_bf16 v[98:101], v[154:157], v[198:201], v[98:101]
	v_mfma_f32_16x16x32_bf16 v[86:89], v[146:149], v[206:209], v[86:89]
	v_mfma_f32_16x16x32_bf16 v[82:85], v[154:157], v[206:209], v[82:85]
	v_mfma_f32_16x16x32_bf16 v[126:129], v[150:153], v[186:189], v[126:129]
	v_mfma_f32_16x16x32_bf16 v[122:125], v[158:161], v[186:189], v[122:125]
	v_mfma_f32_16x16x32_bf16 v[118:121], v[150:153], v[194:197], v[118:121]
	v_mfma_f32_16x16x32_bf16 v[114:117], v[158:161], v[194:197], v[114:117]
	v_mfma_f32_16x16x32_bf16 v[102:105], v[150:153], v[202:205], v[102:105]
	v_mfma_f32_16x16x32_bf16 v[98:101], v[158:161], v[202:205], v[98:101]
	v_mfma_f32_16x16x32_bf16 v[86:89], v[150:153], v[210:213], v[86:89]
	v_mfma_f32_16x16x32_bf16 v[82:85], v[158:161], v[210:213], v[82:85]
	s_setprio 0
	s_setprio 1
	v_mfma_f32_16x16x32_bf16 v[110:113], v[162:165], v[182:185], v[110:113]
	v_mfma_f32_16x16x32_bf16 v[106:109], v[170:173], v[182:185], v[106:109]
	v_mfma_f32_16x16x32_bf16 v[94:97], v[162:165], v[190:193], v[94:97]
	v_mfma_f32_16x16x32_bf16 v[90:93], v[170:173], v[190:193], v[90:93]
	v_mfma_f32_16x16x32_bf16 v[78:81], v[162:165], v[198:201], v[78:81]
	v_mfma_f32_16x16x32_bf16 v[74:77], v[170:173], v[198:201], v[74:77]
	v_mfma_f32_16x16x32_bf16 v[70:73], v[162:165], v[206:209], v[70:73]
	v_mfma_f32_16x16x32_bf16 v[66:69], v[170:173], v[206:209], v[66:69]
	v_mfma_f32_16x16x32_bf16 v[110:113], v[166:169], v[186:189], v[110:113]
	v_mfma_f32_16x16x32_bf16 v[106:109], v[178:181], v[186:189], v[106:109]
	v_mfma_f32_16x16x32_bf16 v[94:97], v[166:169], v[194:197], v[94:97]
	v_mfma_f32_16x16x32_bf16 v[90:93], v[178:181], v[194:197], v[90:93]
	v_mfma_f32_16x16x32_bf16 v[78:81], v[166:169], v[202:205], v[78:81]
	v_mfma_f32_16x16x32_bf16 v[74:77], v[178:181], v[202:205], v[74:77]
	v_mfma_f32_16x16x32_bf16 v[70:73], v[166:169], v[210:213], v[70:73]
	v_mfma_f32_16x16x32_bf16 v[66:69], v[178:181], v[210:213], v[66:69]
	s_setprio 0
	s_barrier
; #define PG8_STAGE(bufoff, gbase, voff) do { _Pragma("unroll") for (int _i = 0; _i < 2; ++_i) \
;         __builtin_amdgcn_global_load_lds((const unsigned*)((const char*)(gbase) + (voff)[_i]), (LAS unsigned*)(lds + (bufoff) + ldsw + _i * 8192), 16, 0, 0); } while (0)
; #define PG8_LDA(dst, b, h) do { _Pragma("unroll") for (int m = 0; m < 4; ++m) _Pragma("unroll") for (int k = 0; k < 2; ++k) dst[m][k] = *(const LAS bf16x8*)(lds + PG8_SA(b, h) + aoff + m * 2048 + k * 1024); } while (0)
; #define PG8_MMA(ai, bj, At, Bt) do { __builtin_amdgcn_s_setprio(1); _Pragma("unroll") for (int m = 0; m < 4; ++m) _Pragma("unroll") for (int n = 0; n < 2; ++n) _Pragma("unroll") for (int k = 0; k < 2; ++k) \
;         acc[ai][bj][m][n] = __builtin_amdgcn_mfma_f32_16x16x32_bf16(Bt[n][k], At[m][k], acc[ai][bj][m][n], 0, 0, 0); __builtin_amdgcn_s_setprio(0); } while (0)
; #define PG8_WAIT_V(n) asm volatile("s_waitcnt vmcnt(" #n ")" ::: "memory")
; #define PG8_WAIT_L(n) asm volatile("s_waitcnt lgkmcnt(" #n ")" ::: "memory")
; #define PG8_BAR __builtin_amdgcn_s_barrier()
; #define PG8_SCHED __builtin_amdgcn_sched_barrier(0)
; template <class Epi>
; __device__ __forceinline__ void gemm_phase(LAS unsigned char* lds, const Gemm g, const StaticOrder& S, const Epi& E, int wave_s) {
;     ...
;             PG8_LDA(At, 1, 1); PG8_STAGE(PG8_SB(1, 0), b3, voffB); PG8_STAGE(PG8_SB(1, 1), b3 + hstepB, voffB); PG8_STAGE(PG8_SA(1, 0), a3, voffA);
;             PG8_WAIT_V(8); PG8_WAIT_L(0); PG8_BAR; PG8_MMA(1, 0, At, B0); PG8_MMA(1, 1, At, B1); PG8_BAR; PG8_SCHED;
;         }
	s_add_i32 s30, s53, s36
	v_lshl_add_u64 v[174:175], v[174:175], 0, s[84:85]
	s_mov_b32 m0, s30
	ds_read_b128 v[182:185], v144 offset:49152
	ds_read_b128 v[186:189], v144 offset:50176
	ds_read_b128 v[190:193], v144 offset:51200
	ds_read_b128 v[194:197], v144 offset:52224
	ds_read_b128 v[198:201], v144 offset:53248
	ds_read_b128 v[202:205], v144 offset:54272
	ds_read_b128 v[206:209], v144 offset:55296
	ds_read_b128 v[210:213], v144 offset:56320
	global_load_lds_dwordx4 v[174:175], off
	s_add_i32 m0, s30, 0x2000
	s_add_u32 s26, s26, 0x40080
	v_lshl_add_u64 v[174:175], v[176:177], 0, s[84:85]
	s_addc_u32 s27, s27, 0
	s_add_i32 s30, s54, s36
	global_load_lds_dwordx4 v[174:175], off
	v_lshl_add_u64 v[174:175], s[26:27], 0, v[134:135]
	s_mov_b32 m0, s30
	s_nop 0
	global_load_lds_dwordx4 v[174:175], off
	v_lshl_add_u64 v[174:175], s[26:27], 0, v[130:131]
	s_add_i32 m0, s30, 0x2000
	s_nop 0
	global_load_lds_dwordx4 v[174:175], off
	v_lshl_add_u64 v[174:175], v[214:215], 0, s[84:85]
	s_mov_b32 m0, s43
	s_nop 0
	global_load_lds_dwordx4 v[174:175], off
	v_lshl_add_u64 v[174:175], v[216:217], 0, s[84:85]
	s_mov_b32 m0, s44
	s_nop 0
	global_load_lds_dwordx4 v[174:175], off
	s_waitcnt vmcnt(8)
	s_waitcnt lgkmcnt(0)
	s_barrier
	s_setprio 1
	s_waitcnt lgkmcnt(0)
	v_mfma_f32_16x16x32_bf16 v[62:65], v[146:149], v[182:185], v[62:65]
	v_mfma_f32_16x16x32_bf16 v[58:61], v[154:157], v[182:185], v[58:61]
	v_mfma_f32_16x16x32_bf16 v[54:57], v[146:149], v[190:193], v[54:57]
	v_mfma_f32_16x16x32_bf16 v[50:53], v[154:157], v[190:193], v[50:53]
	v_mfma_f32_16x16x32_bf16 v[38:41], v[146:149], v[198:201], v[38:41]
	v_mfma_f32_16x16x32_bf16 v[34:37], v[154:157], v[198:201], v[34:37]
	v_mfma_f32_16x16x32_bf16 v[22:25], v[146:149], v[206:209], v[22:25]
	v_mfma_f32_16x16x32_bf16 v[18:21], v[154:157], v[206:209], v[18:21]
	v_mfma_f32_16x16x32_bf16 v[62:65], v[150:153], v[186:189], v[62:65]
	v_mfma_f32_16x16x32_bf16 v[58:61], v[158:161], v[186:189], v[58:61]
	v_mfma_f32_16x16x32_bf16 v[54:57], v[150:153], v[194:197], v[54:57]
	v_mfma_f32_16x16x32_bf16 v[50:53], v[158:161], v[194:197], v[50:53]
	v_mfma_f32_16x16x32_bf16 v[38:41], v[150:153], v[202:205], v[38:41]
	v_mfma_f32_16x16x32_bf16 v[34:37], v[158:161], v[202:205], v[34:37]
	v_mfma_f32_16x16x32_bf16 v[22:25], v[150:153], v[210:213], v[22:25]
	v_mfma_f32_16x16x32_bf16 v[18:21], v[158:161], v[210:213], v[18:21]
	s_setprio 0
	s_setprio 1
	v_mfma_f32_16x16x32_bf16 v[46:49], v[162:165], v[182:185], v[46:49]
	v_mfma_f32_16x16x32_bf16 v[42:45], v[170:173], v[182:185], v[42:45]
	v_mfma_f32_16x16x32_bf16 v[30:33], v[162:165], v[190:193], v[30:33]
	v_mfma_f32_16x16x32_bf16 v[26:29], v[170:173], v[190:193], v[26:29]
	v_mfma_f32_16x16x32_bf16 v[14:17], v[162:165], v[198:201], v[14:17]
	v_mfma_f32_16x16x32_bf16 v[8:11], v[170:173], v[198:201], v[8:11]
	v_mfma_f32_16x16x32_bf16 v[4:7], v[162:165], v[206:209], v[4:7]
	v_mfma_f32_16x16x32_bf16 v[0:3], v[170:173], v[206:209], v[0:3]
	v_mfma_f32_16x16x32_bf16 v[46:49], v[166:169], v[186:189], v[46:49]
	v_mfma_f32_16x16x32_bf16 v[42:45], v[178:181], v[186:189], v[42:45]
	v_mfma_f32_16x16x32_bf16 v[30:33], v[166:169], v[194:197], v[30:33]
	v_mfma_f32_16x16x32_bf16 v[26:29], v[178:181], v[194:197], v[26:29]
	v_mfma_f32_16x16x32_bf16 v[14:17], v[166:169], v[202:205], v[14:17]
	v_mfma_f32_16x16x32_bf16 v[8:11], v[178:181], v[202:205], v[8:11]
	v_mfma_f32_16x16x32_bf16 v[4:7], v[166:169], v[210:213], v[4:7]
	v_mfma_f32_16x16x32_bf16 v[0:3], v[178:181], v[210:213], v[0:3]
	s_setprio 0
	s_barrier
	s_add_i32 s52, s52, 2
	s_add_u32 s22, s22, 0x100
	s_addc_u32 s23, s23, 0
	s_add_u32 s50, s50, 0x100
	s_addc_u32 s51, s51, 0
	s_cmp_gt_u32 s52, 13
	s_cbranch_scc0 .LBB0_1044
	s_branch .Lg6_after
